# attnA step loop: K/V LDS-DMA issue uses SGPR base + per-lane voffset and M0 = wave-base SGPR + constant (removes ~14 VALU ops per step)
# baseline (speedup 1.0000x reference)
.LBB0_1367:
	v_readfirstlane_b32 s38, v202
	s_add_i32 s16, s34, 2
	s_cmp_lt_u32 s34, s29
	s_cselect_b64 s[20:21], -1, 0
	s_cmp_ge_u32 s34, s29
	s_cselect_b64 s[18:19], -1, 0
	s_and_b64 vcc, exec, s[18:19]
	s_cbranch_vccnz .LBB0_1369
	s_mov_b32 s17, s83
	s_lshl_b64 s[4:5], s[16:17], 18
	s_add_u32 s4, s6, s4
	s_addc_u32 s5, s7, s5
	s_add_u32 s4, s4, s84
	s_addc_u32 s5, s5, s85
	s_mov_b32 m0, s38
	s_nop 0
	global_load_lds_dwordx4 v196, s[4:5]
	s_add_u32 m0, s38, 0x1000
	s_nop 0
	global_load_lds_dwordx4 v197, s[4:5]
.LBB0_1369:
	s_or_b32 s82, s34, 1
	s_lshl_b64 s[4:5], s[82:83], 7
	s_add_u32 s4, s8, s4
	s_addc_u32 s5, s9, s5
	s_add_u32 m0, s38, 0x8000
	s_nop 0
	global_load_lds_dwordx4 v198, s[4:5]
	s_add_u32 m0, s38, 0x9000
	s_nop 0
	global_load_lds_dwordx4 v199, s[4:5]
	s_add_u32 m0, s38, 0xa000
	s_nop 0
	global_load_lds_dwordx4 v200, s[4:5]
	s_add_u32 m0, s38, 0xb000
	s_nop 0
	global_load_lds_dwordx4 v201, s[4:5]
	v_cmp_lt_i32_e64 s[4:5], s34, v226
	s_and_saveexec_b64 s[22:23], s[4:5]
	s_cbranch_execz .LBB0_1371
	ds_read_b128 v[2:5], v222 offset:24576
	ds_read_b128 v[6:9], v222 offset:28672
	ds_read_b128 v[10:13], v223 offset:24576
	ds_read_b128 v[244:247], v223 offset:28672
	s_waitcnt lgkmcnt(3)
	v_mfma_f32_32x32x16_bf16 v[128:143], v[2:5], v[160:163], v[16:31]
	ds_read_b128 v[2:5], v224 offset:24576
	s_waitcnt lgkmcnt(3)
	v_mfma_f32_32x32x16_bf16 v[144:159], v[6:9], v[160:163], v[16:31]
	ds_read_b128 v[6:9], v224 offset:28672
	s_waitcnt lgkmcnt(3)
	v_mfma_f32_32x32x16_bf16 v[128:143], v[10:13], v[164:167], v[128:143]
	ds_read_b128 v[10:13], v225 offset:24576
	s_waitcnt lgkmcnt(3)
	v_mfma_f32_32x32x16_bf16 v[144:159], v[244:247], v[164:167], v[144:159]
	ds_read_b128 v[244:247], v225 offset:28672
	s_waitcnt lgkmcnt(3)
	v_mfma_f32_32x32x16_bf16 v[128:143], v[2:5], v[168:171], v[128:143]
	s_waitcnt lgkmcnt(2)
	v_mfma_f32_32x32x16_bf16 v[144:159], v[6:9], v[168:171], v[144:159]
	s_waitcnt lgkmcnt(1)
	v_mfma_f32_32x32x16_bf16 v[128:143], v[10:13], v[172:175], v[128:143]
	s_waitcnt lgkmcnt(0)
	v_mfma_f32_32x32x16_bf16 v[144:159], v[244:247], v[172:175], v[144:159]

.LBB0_1378:
	s_add_i32 s82, s34, 3
	s_cmp_ge_u32 s82, s30
	s_cbranch_scc1 .LBB0_1382
	s_lshl_b64 s[22:23], s[82:83], 18
	s_add_u32 s22, s6, s22
	s_addc_u32 s23, s7, s23
	s_add_u32 s22, s22, s84
	s_addc_u32 s23, s23, s85
	s_add_u32 m0, s38, 0x6000
	s_nop 0
	global_load_lds_dwordx4 v196, s[22:23]
	s_add_u32 m0, s38, 0x7000
	s_nop 0
	global_load_lds_dwordx4 v197, s[22:23]
	s_andn2_b64 vcc, exec, s[20:21]
	s_cbranch_vccz .LBB0_1383

.LBB0_1383:
	s_mov_b32 s17, s83
	s_lshl_b64 s[20:21], s[16:17], 7
	s_add_u32 s20, s8, s20
	s_addc_u32 s21, s9, s21
	s_add_u32 m0, s38, 0x2000
	s_nop 0
	global_load_lds_dwordx4 v198, s[20:21]
	s_add_u32 m0, s38, 0x3000
	s_nop 0
	global_load_lds_dwordx4 v199, s[20:21]
	s_add_u32 m0, s38, 0x4000
	s_nop 0
	global_load_lds_dwordx4 v200, s[20:21]
	s_add_u32 m0, s38, 0x5000
	s_nop 0
	global_load_lds_dwordx4 v201, s[20:21]
	v_cmp_le_i32_e32 vcc, s16, v226
	s_and_saveexec_b64 s[20:21], vcc
	s_cbranch_execnz .LBB0_1381

.LBB0_1409:
	v_readfirstlane_b32 s38, v200
	s_add_i32 s16, s31, 2
	s_cmp_lt_u32 s31, s29
	s_cselect_b64 s[20:21], -1, 0
	s_cmp_ge_u32 s31, s29
	s_cselect_b64 s[18:19], -1, 0
	s_and_b64 vcc, exec, s[18:19]
	s_cbranch_vccnz .LBB0_1411
	s_mov_b32 s17, s83
	s_lshl_b64 s[4:5], s[16:17], 18
	s_add_u32 s4, s6, s4
	s_addc_u32 s5, s7, s5
	s_add_u32 s4, s4, s86
	s_addc_u32 s5, s5, s87
	s_mov_b32 m0, s38
	s_nop 0
	global_load_lds_dwordx4 v186, s[4:5]
	s_add_u32 m0, s38, 0x1000
	s_nop 0
	global_load_lds_dwordx4 v187, s[4:5]
.LBB0_1411:
	s_or_b32 s82, s31, 1
	s_lshl_b64 s[4:5], s[82:83], 7
	s_add_u32 s4, s8, s4
	s_addc_u32 s5, s9, s5
	s_add_u32 m0, s38, 0x8000
	s_nop 0
	global_load_lds_dwordx4 v196, s[4:5]
	s_add_u32 m0, s38, 0x9000
	s_nop 0
	global_load_lds_dwordx4 v197, s[4:5]
	s_add_u32 m0, s38, 0xa000
	s_nop 0
	global_load_lds_dwordx4 v198, s[4:5]
	s_add_u32 m0, s38, 0xb000
	s_nop 0
	global_load_lds_dwordx4 v199, s[4:5]
	v_cmp_lt_i32_e64 s[4:5], s31, v225
	s_and_saveexec_b64 s[22:23], s[4:5]
	s_cbranch_execz .LBB0_1413
	ds_read_b128 v[2:5], v220 offset:24576
	ds_read_b128 v[6:9], v220 offset:28672
	ds_read_b128 v[10:13], v221 offset:24576
	ds_read_b128 v[244:247], v221 offset:28672
	s_waitcnt lgkmcnt(3)
	v_mfma_f32_32x32x16_bf16 v[128:143], v[2:5], v[160:163], v[16:31]
	ds_read_b128 v[2:5], v222 offset:24576
	s_waitcnt lgkmcnt(3)
	v_mfma_f32_32x32x16_bf16 v[144:159], v[6:9], v[160:163], v[16:31]
	ds_read_b128 v[6:9], v222 offset:28672
	s_waitcnt lgkmcnt(3)
	v_mfma_f32_32x32x16_bf16 v[128:143], v[10:13], v[164:167], v[128:143]
	ds_read_b128 v[10:13], v223 offset:24576
	s_waitcnt lgkmcnt(3)
	v_mfma_f32_32x32x16_bf16 v[144:159], v[244:247], v[164:167], v[144:159]
	ds_read_b128 v[244:247], v223 offset:28672
	s_waitcnt lgkmcnt(3)
	v_mfma_f32_32x32x16_bf16 v[128:143], v[2:5], v[168:171], v[128:143]
	s_waitcnt lgkmcnt(2)
	v_mfma_f32_32x32x16_bf16 v[144:159], v[6:9], v[168:171], v[144:159]
	s_waitcnt lgkmcnt(1)
	v_mfma_f32_32x32x16_bf16 v[128:143], v[10:13], v[172:175], v[128:143]
	s_waitcnt lgkmcnt(0)
	v_mfma_f32_32x32x16_bf16 v[144:159], v[244:247], v[172:175], v[144:159]

.LBB0_1420:
	s_add_i32 s82, s31, 3
	s_cmp_ge_u32 s82, s30
	s_cbranch_scc1 .LBB0_1424
	s_lshl_b64 s[22:23], s[82:83], 18
	s_add_u32 s22, s6, s22
	s_addc_u32 s23, s7, s23
	s_add_u32 s22, s22, s86
	s_addc_u32 s23, s23, s87
	s_add_u32 m0, s38, 0x6000
	s_nop 0
	global_load_lds_dwordx4 v186, s[22:23]
	s_add_u32 m0, s38, 0x7000
	s_nop 0
	global_load_lds_dwordx4 v187, s[22:23]
	s_andn2_b64 vcc, exec, s[20:21]
	s_cbranch_vccz .LBB0_1425

.LBB0_1425:
	s_mov_b32 s17, s83
	s_lshl_b64 s[20:21], s[16:17], 7
	s_add_u32 s20, s8, s20
	s_addc_u32 s21, s9, s21
	s_add_u32 m0, s38, 0x2000
	s_nop 0
	global_load_lds_dwordx4 v196, s[20:21]
	s_add_u32 m0, s38, 0x3000
	s_nop 0
	global_load_lds_dwordx4 v197, s[20:21]
	s_add_u32 m0, s38, 0x4000
	s_nop 0
	global_load_lds_dwordx4 v198, s[20:21]
	s_add_u32 m0, s38, 0x5000
	s_nop 0
	global_load_lds_dwordx4 v199, s[20:21]
	v_cmp_le_i32_e32 vcc, s16, v225
	s_and_saveexec_b64 s[20:21], vcc
	s_cbranch_execnz .LBB0_1423
